# FFN up/down K-loops: LDS fragment-read base addresses hoisted out of the loop (no VALU left in the load phases) on top of SGPR-base LDS-DMA addressing
# baseline (speedup 1.0000x reference)
.LBB0_586:
	s_xor_b64 s[46:47], s[64:65], -1
	s_add_u32 s21, s30, 0x100
	s_addc_u32 s74, s31, 0
	s_ashr_i32 s45, s44, 31
	s_lshl_b64 s[16:17], s[44:45], 20
	s_add_u32 s38, s54, s16
	s_addc_u32 s39, s55, s17
	s_and_b64 s[16:17], s[64:65], exec
	s_cselect_b32 s61, s39, s53
	s_cselect_b32 s60, s38, s52
	s_ashr_i32 s51, s50, 31
	s_lshl_b64 s[16:17], s[50:51], 20
	s_add_u32 s38, s56, s16
	s_addc_u32 s39, s57, s17
	s_and_b64 s[16:17], s[64:65], exec
	s_cselect_b32 s31, s39, s31
	s_cselect_b32 s30, s38, s30
	s_add_u32 s16, s52, 0x80080
	s_addc_u32 s17, s53, 0
	v_lshl_add_u64 v[134:135], s[16:17], 0, v[148:149]
	v_lshl_add_u64 v[136:137], s[16:17], 0, v[150:151]
	v_add_u32_e32 v200, 0x10000, v157
	v_add_u32_e32 v201, 0x14000, v157
	v_add_u32_e32 v202, 0x18000, v157
	v_add_u32_e32 v203, 0x1c000, v157
	s_mov_b32 s40, -2
.LBB0_587:
	s_add_u32 s90, s52, s4
	s_addc_u32 s91, s53, s5
	s_add_u32 s90, s90, 0x80080
	s_addc_u32 s91, s91, 0
	s_add_u32 s16, s52, s4
	s_addc_u32 s17, s53, s5
	s_add_u32 s16, s16, 0x100
	s_addc_u32 s17, s17, 0
	s_add_u32 s41, s21, s4
	s_addc_u32 s45, s74, s5
	s_add_i32 s51, 0, 0x10000
	s_cmpk_eq_i32 s4, 0xf00
	s_cselect_b32 s39, s61, s17
	s_cselect_b32 s38, s60, s16
	s_cselect_b32 s17, s31, s45
	s_cselect_b32 s16, s30, s41
	s_add_i32 s41, 0, 0x14000
	ds_read_b128 v[138:141], v200
	ds_read_b128 v[152:155], v200 offset:1024
	ds_read_b128 v[158:161], v200 offset:2048
	ds_read_b128 v[164:167], v200 offset:3072
	ds_read_b128 v[170:173], v201
	ds_read_b128 v[174:177], v201 offset:1024
	ds_read_b128 v[178:181], v201 offset:2048
	ds_read_b128 v[186:189], v201 offset:3072
	s_add_i32 m0, s58, 0xc000
	ds_read_b128 v[190:193], v184
	ds_read_b128 v[194:197], v184 offset:1024
	ds_read_b128 v[204:207], v184 offset:2048
	ds_read_b128 v[208:211], v184 offset:3072
	ds_read_b128 v[212:215], v184 offset:4096
	ds_read_b128 v[216:219], v184 offset:5120
	ds_read_b128 v[220:223], v184 offset:6144
	ds_read_b128 v[224:227], v184 offset:7168
	global_load_lds_dwordx4 v150, s[90:91]
	s_add_i32 m0, s58, 0xe000
	s_nop 0
	global_load_lds_dwordx4 v148, s[90:91]
	s_waitcnt vmcnt(8)
	s_waitcnt lgkmcnt(0)
	s_setprio 1
	s_barrier
	v_mfma_f32_16x16x32_bf16 v[6:9], v[138:141], v[190:193], v[6:9]
	v_mfma_f32_16x16x32_bf16 v[130:133], v[158:161], v[190:193], v[130:133]
	v_mfma_f32_16x16x32_bf16 v[126:129], v[138:141], v[204:207], v[126:129]
	v_mfma_f32_16x16x32_bf16 v[122:125], v[158:161], v[204:207], v[122:125]
	v_mfma_f32_16x16x32_bf16 v[118:121], v[138:141], v[212:215], v[118:121]
	v_mfma_f32_16x16x32_bf16 v[114:117], v[158:161], v[212:215], v[114:117]
	v_mfma_f32_16x16x32_bf16 v[110:113], v[138:141], v[220:223], v[110:113]
	v_mfma_f32_16x16x32_bf16 v[106:109], v[158:161], v[220:223], v[106:109]
	v_mfma_f32_16x16x32_bf16 v[6:9], v[152:155], v[194:197], v[6:9]
	v_mfma_f32_16x16x32_bf16 v[130:133], v[164:167], v[194:197], v[130:133]
	v_mfma_f32_16x16x32_bf16 v[126:129], v[152:155], v[208:211], v[126:129]
	v_mfma_f32_16x16x32_bf16 v[122:125], v[164:167], v[208:211], v[122:125]
	v_mfma_f32_16x16x32_bf16 v[118:121], v[152:155], v[216:219], v[118:121]
	v_mfma_f32_16x16x32_bf16 v[114:117], v[164:167], v[216:219], v[114:117]
	v_mfma_f32_16x16x32_bf16 v[110:113], v[152:155], v[224:227], v[110:113]
	v_mfma_f32_16x16x32_bf16 v[106:109], v[164:167], v[224:227], v[106:109]
	v_mfma_f32_16x16x32_bf16 v[102:105], v[170:173], v[190:193], v[102:105]
	v_mfma_f32_16x16x32_bf16 v[98:101], v[178:181], v[190:193], v[98:101]
	v_mfma_f32_16x16x32_bf16 v[94:97], v[170:173], v[204:207], v[94:97]
	v_mfma_f32_16x16x32_bf16 v[90:93], v[178:181], v[204:207], v[90:93]
	v_mfma_f32_16x16x32_bf16 v[86:89], v[170:173], v[212:215], v[86:89]
	v_mfma_f32_16x16x32_bf16 v[82:85], v[178:181], v[212:215], v[82:85]
	v_mfma_f32_16x16x32_bf16 v[78:81], v[170:173], v[220:223], v[78:81]
	v_mfma_f32_16x16x32_bf16 v[74:77], v[178:181], v[220:223], v[74:77]
	v_mfma_f32_16x16x32_bf16 v[102:105], v[174:177], v[194:197], v[102:105]
	v_mfma_f32_16x16x32_bf16 v[98:101], v[186:189], v[194:197], v[98:101]
	v_mfma_f32_16x16x32_bf16 v[94:97], v[174:177], v[208:211], v[94:97]
	v_mfma_f32_16x16x32_bf16 v[90:93], v[186:189], v[208:211], v[90:93]
	v_mfma_f32_16x16x32_bf16 v[86:89], v[174:177], v[216:219], v[86:89]
	v_mfma_f32_16x16x32_bf16 v[82:85], v[186:189], v[216:219], v[82:85]
	v_mfma_f32_16x16x32_bf16 v[78:81], v[174:177], v[224:227], v[78:81]
	v_mfma_f32_16x16x32_bf16 v[74:77], v[186:189], v[224:227], v[74:77]
	s_barrier
	s_setprio 0
	s_add_i32 s45, s51, s49
	s_mov_b32 m0, s45
	ds_read_b128 v[190:193], v184 offset:16384
	ds_read_b128 v[194:197], v184 offset:17408
	ds_read_b128 v[204:207], v184 offset:18432
	ds_read_b128 v[208:211], v184 offset:19456
	ds_read_b128 v[212:215], v184 offset:20480
	ds_read_b128 v[216:219], v184 offset:21504
	ds_read_b128 v[220:223], v184 offset:22528
	ds_read_b128 v[224:227], v184 offset:23552
	global_load_lds_dwordx4 v0, s[16:17]
	s_add_i32 m0, s45, 0x2000
	s_add_u32 s76, s16, 0x80000
	s_addc_u32 s77, s17, 0
	s_add_i32 s41, s41, s49
	global_load_lds_dwordx4 v144, s[16:17]
	s_mov_b32 m0, s41
	s_add_u32 s92, s38, s96
	s_addc_u32 s93, s39, s97
	global_load_lds_dwordx4 v0, s[76:77]
	s_add_i32 m0, s41, 0x2000
	s_nop 0
	global_load_lds_dwordx4 v144, s[76:77]
	s_mov_b32 m0, s58
	s_nop 0
	global_load_lds_dwordx4 v14, s[38:39]
	s_mov_b32 m0, s59
	s_nop 0
	global_load_lds_dwordx4 v142, s[38:39]
	s_waitcnt vmcnt(8)
	s_waitcnt lgkmcnt(0)
	s_setprio 1
	s_barrier
	v_mfma_f32_16x16x32_bf16 v[70:73], v[138:141], v[190:193], v[70:73]
	v_mfma_f32_16x16x32_bf16 v[66:69], v[158:161], v[190:193], v[66:69]
	v_mfma_f32_16x16x32_bf16 v[62:65], v[138:141], v[204:207], v[62:65]
	v_mfma_f32_16x16x32_bf16 v[58:61], v[158:161], v[204:207], v[58:61]
	v_mfma_f32_16x16x32_bf16 v[54:57], v[138:141], v[212:215], v[54:57]
	v_mfma_f32_16x16x32_bf16 v[50:53], v[158:161], v[212:215], v[50:53]
	v_mfma_f32_16x16x32_bf16 v[46:49], v[138:141], v[220:223], v[46:49]
	v_mfma_f32_16x16x32_bf16 v[42:45], v[158:161], v[220:223], v[42:45]
	v_mfma_f32_16x16x32_bf16 v[70:73], v[152:155], v[194:197], v[70:73]
	v_mfma_f32_16x16x32_bf16 v[66:69], v[164:167], v[194:197], v[66:69]
	v_mfma_f32_16x16x32_bf16 v[62:65], v[152:155], v[208:211], v[62:65]
	v_mfma_f32_16x16x32_bf16 v[58:61], v[164:167], v[208:211], v[58:61]
	v_mfma_f32_16x16x32_bf16 v[54:57], v[152:155], v[216:219], v[54:57]
	v_mfma_f32_16x16x32_bf16 v[50:53], v[164:167], v[216:219], v[50:53]
	v_mfma_f32_16x16x32_bf16 v[46:49], v[152:155], v[224:227], v[46:49]
	v_mfma_f32_16x16x32_bf16 v[42:45], v[164:167], v[224:227], v[42:45]
	v_mfma_f32_16x16x32_bf16 v[38:41], v[170:173], v[190:193], v[38:41]
	v_mfma_f32_16x16x32_bf16 v[34:37], v[178:181], v[190:193], v[34:37]
	v_mfma_f32_16x16x32_bf16 v[30:33], v[170:173], v[204:207], v[30:33]
	v_mfma_f32_16x16x32_bf16 v[26:29], v[178:181], v[204:207], v[26:29]
	v_mfma_f32_16x16x32_bf16 v[22:25], v[170:173], v[212:215], v[22:25]
	v_mfma_f32_16x16x32_bf16 v[18:21], v[178:181], v[212:215], v[18:21]
	v_mfma_f32_16x16x32_bf16 v[10:13], v[170:173], v[220:223], v[10:13]
	v_mfma_f32_16x16x32_bf16 v[2:5], v[178:181], v[220:223], v[2:5]
	v_mfma_f32_16x16x32_bf16 v[38:41], v[174:177], v[194:197], v[38:41]
	v_mfma_f32_16x16x32_bf16 v[34:37], v[186:189], v[194:197], v[34:37]
	v_mfma_f32_16x16x32_bf16 v[30:33], v[174:177], v[208:211], v[30:33]
	v_mfma_f32_16x16x32_bf16 v[26:29], v[186:189], v[208:211], v[26:29]
	v_mfma_f32_16x16x32_bf16 v[22:25], v[174:177], v[216:219], v[22:25]
	v_mfma_f32_16x16x32_bf16 v[18:21], v[186:189], v[216:219], v[18:21]
	v_mfma_f32_16x16x32_bf16 v[10:13], v[174:177], v[224:227], v[10:13]
	v_mfma_f32_16x16x32_bf16 v[2:5], v[186:189], v[224:227], v[2:5]
	s_barrier
	s_setprio 0
	s_add_i32 s41, 0, 0x18000
	s_add_i32 s45, 0, 0x1c000
	ds_read_b128 v[138:141], v202
	ds_read_b128 v[152:155], v202 offset:1024
	ds_read_b128 v[158:161], v202 offset:2048
	ds_read_b128 v[164:167], v202 offset:3072
	ds_read_b128 v[170:173], v203
	ds_read_b128 v[174:177], v203 offset:1024
	ds_read_b128 v[178:181], v203 offset:2048
	ds_read_b128 v[186:189], v203 offset:3072
	s_add_u32 s38, s38, 0x80000
	s_addc_u32 s39, s39, 0
	s_mov_b32 m0, s62
	ds_read_b128 v[190:193], v184 offset:32768
	ds_read_b128 v[194:197], v184 offset:33792
	ds_read_b128 v[204:207], v184 offset:34816
	ds_read_b128 v[208:211], v184 offset:35840
	ds_read_b128 v[212:215], v184 offset:36864
	ds_read_b128 v[216:219], v184 offset:37888
	ds_read_b128 v[220:223], v184 offset:38912
	ds_read_b128 v[224:227], v184 offset:39936
	global_load_lds_dwordx4 v14, s[38:39]
	s_mov_b32 m0, s63
	s_nop 0
	global_load_lds_dwordx4 v142, s[38:39]
	s_waitcnt vmcnt(8)
	s_waitcnt lgkmcnt(0)
	s_setprio 1
	s_barrier
	v_mfma_f32_16x16x32_bf16 v[6:9], v[138:141], v[190:193], v[6:9]
	v_mfma_f32_16x16x32_bf16 v[130:133], v[158:161], v[190:193], v[130:133]
	v_mfma_f32_16x16x32_bf16 v[126:129], v[138:141], v[204:207], v[126:129]
	v_mfma_f32_16x16x32_bf16 v[122:125], v[158:161], v[204:207], v[122:125]
	v_mfma_f32_16x16x32_bf16 v[118:121], v[138:141], v[212:215], v[118:121]
	v_mfma_f32_16x16x32_bf16 v[114:117], v[158:161], v[212:215], v[114:117]
	v_mfma_f32_16x16x32_bf16 v[110:113], v[138:141], v[220:223], v[110:113]
	v_mfma_f32_16x16x32_bf16 v[106:109], v[158:161], v[220:223], v[106:109]
	v_mfma_f32_16x16x32_bf16 v[6:9], v[152:155], v[194:197], v[6:9]
	v_mfma_f32_16x16x32_bf16 v[130:133], v[164:167], v[194:197], v[130:133]
	v_mfma_f32_16x16x32_bf16 v[126:129], v[152:155], v[208:211], v[126:129]
	v_mfma_f32_16x16x32_bf16 v[122:125], v[164:167], v[208:211], v[122:125]
	v_mfma_f32_16x16x32_bf16 v[118:121], v[152:155], v[216:219], v[118:121]
	v_mfma_f32_16x16x32_bf16 v[114:117], v[164:167], v[216:219], v[114:117]
	v_mfma_f32_16x16x32_bf16 v[110:113], v[152:155], v[224:227], v[110:113]
	v_mfma_f32_16x16x32_bf16 v[106:109], v[164:167], v[224:227], v[106:109]
	v_mfma_f32_16x16x32_bf16 v[102:105], v[170:173], v[190:193], v[102:105]
	v_mfma_f32_16x16x32_bf16 v[98:101], v[178:181], v[190:193], v[98:101]
	v_mfma_f32_16x16x32_bf16 v[94:97], v[170:173], v[204:207], v[94:97]
	v_mfma_f32_16x16x32_bf16 v[90:93], v[178:181], v[204:207], v[90:93]
	v_mfma_f32_16x16x32_bf16 v[86:89], v[170:173], v[212:215], v[86:89]
	v_mfma_f32_16x16x32_bf16 v[82:85], v[178:181], v[212:215], v[82:85]
	v_mfma_f32_16x16x32_bf16 v[78:81], v[170:173], v[220:223], v[78:81]
	v_mfma_f32_16x16x32_bf16 v[74:77], v[178:181], v[220:223], v[74:77]
	v_mfma_f32_16x16x32_bf16 v[102:105], v[174:177], v[194:197], v[102:105]
	v_mfma_f32_16x16x32_bf16 v[98:101], v[186:189], v[194:197], v[98:101]
	v_mfma_f32_16x16x32_bf16 v[94:97], v[174:177], v[208:211], v[94:97]
	v_mfma_f32_16x16x32_bf16 v[90:93], v[186:189], v[208:211], v[90:93]
	v_mfma_f32_16x16x32_bf16 v[86:89], v[174:177], v[216:219], v[86:89]
	v_mfma_f32_16x16x32_bf16 v[82:85], v[186:189], v[216:219], v[82:85]
	v_mfma_f32_16x16x32_bf16 v[78:81], v[174:177], v[224:227], v[78:81]
	v_mfma_f32_16x16x32_bf16 v[74:77], v[186:189], v[224:227], v[74:77]
	s_barrier
	s_setprio 0
	s_add_i32 s38, s41, s49
	s_add_u32 s90, s16, s96
	s_addc_u32 s91, s17, s97
	s_mov_b32 m0, s38
	ds_read_b128 v[190:193], v184 offset:49152
	ds_read_b128 v[194:197], v184 offset:50176
	ds_read_b128 v[204:207], v184 offset:51200
	ds_read_b128 v[208:211], v184 offset:52224
	ds_read_b128 v[212:215], v184 offset:53248
	ds_read_b128 v[216:219], v184 offset:54272
	ds_read_b128 v[220:223], v184 offset:55296
	ds_read_b128 v[224:227], v184 offset:56320
	global_load_lds_dwordx4 v0, s[90:91]
	s_add_i32 m0, s38, 0x2000
	s_add_u32 s16, s16, 0x80080
	s_addc_u32 s17, s17, 0
	s_add_i32 s38, s45, s49
	global_load_lds_dwordx4 v144, s[90:91]
	s_mov_b32 m0, s38
	s_nop 0
	global_load_lds_dwordx4 v0, s[16:17]
	s_add_i32 m0, s38, 0x2000
	s_nop 0
	global_load_lds_dwordx4 v144, s[16:17]
	s_mov_b32 m0, s68
	s_nop 0
	global_load_lds_dwordx4 v14, s[92:93]
	s_mov_b32 m0, s69
	s_nop 0
	global_load_lds_dwordx4 v142, s[92:93]
	s_waitcnt vmcnt(8)
	s_waitcnt lgkmcnt(0)
	s_setprio 1
	s_barrier
	v_mfma_f32_16x16x32_bf16 v[70:73], v[138:141], v[190:193], v[70:73]
	v_mfma_f32_16x16x32_bf16 v[66:69], v[158:161], v[190:193], v[66:69]
	v_mfma_f32_16x16x32_bf16 v[62:65], v[138:141], v[204:207], v[62:65]
	v_mfma_f32_16x16x32_bf16 v[58:61], v[158:161], v[204:207], v[58:61]
	v_mfma_f32_16x16x32_bf16 v[54:57], v[138:141], v[212:215], v[54:57]
	v_mfma_f32_16x16x32_bf16 v[50:53], v[158:161], v[212:215], v[50:53]
	v_mfma_f32_16x16x32_bf16 v[46:49], v[138:141], v[220:223], v[46:49]
	v_mfma_f32_16x16x32_bf16 v[42:45], v[158:161], v[220:223], v[42:45]
	v_mfma_f32_16x16x32_bf16 v[70:73], v[152:155], v[194:197], v[70:73]
	v_mfma_f32_16x16x32_bf16 v[66:69], v[164:167], v[194:197], v[66:69]
	v_mfma_f32_16x16x32_bf16 v[62:65], v[152:155], v[208:211], v[62:65]
	v_mfma_f32_16x16x32_bf16 v[58:61], v[164:167], v[208:211], v[58:61]
	v_mfma_f32_16x16x32_bf16 v[54:57], v[152:155], v[216:219], v[54:57]
	v_mfma_f32_16x16x32_bf16 v[50:53], v[164:167], v[216:219], v[50:53]
	v_mfma_f32_16x16x32_bf16 v[46:49], v[152:155], v[224:227], v[46:49]
	v_mfma_f32_16x16x32_bf16 v[42:45], v[164:167], v[224:227], v[42:45]
	v_mfma_f32_16x16x32_bf16 v[38:41], v[170:173], v[190:193], v[38:41]
	v_mfma_f32_16x16x32_bf16 v[34:37], v[178:181], v[190:193], v[34:37]
	v_mfma_f32_16x16x32_bf16 v[30:33], v[170:173], v[204:207], v[30:33]
	v_mfma_f32_16x16x32_bf16 v[26:29], v[178:181], v[204:207], v[26:29]
	v_mfma_f32_16x16x32_bf16 v[22:25], v[170:173], v[212:215], v[22:25]
	v_mfma_f32_16x16x32_bf16 v[18:21], v[178:181], v[212:215], v[18:21]
	v_mfma_f32_16x16x32_bf16 v[10:13], v[170:173], v[220:223], v[10:13]
	v_mfma_f32_16x16x32_bf16 v[2:5], v[178:181], v[220:223], v[2:5]
	v_mfma_f32_16x16x32_bf16 v[38:41], v[174:177], v[194:197], v[38:41]
	v_mfma_f32_16x16x32_bf16 v[34:37], v[186:189], v[194:197], v[34:37]
	v_mfma_f32_16x16x32_bf16 v[30:33], v[174:177], v[208:211], v[30:33]
	v_mfma_f32_16x16x32_bf16 v[26:29], v[186:189], v[208:211], v[26:29]
	v_mfma_f32_16x16x32_bf16 v[22:25], v[174:177], v[216:219], v[22:25]
	v_mfma_f32_16x16x32_bf16 v[18:21], v[186:189], v[216:219], v[18:21]
	v_mfma_f32_16x16x32_bf16 v[10:13], v[174:177], v[224:227], v[10:13]
	v_mfma_f32_16x16x32_bf16 v[2:5], v[186:189], v[224:227], v[2:5]
	s_barrier
	s_setprio 0
	s_add_i32 s40, s40, 2
	s_add_u32 s4, s4, 0x100
	s_addc_u32 s5, s5, 0
	s_cmp_gt_u32 s40, 29
	s_cbranch_scc0 .LBB0_587
	s_and_b64 vcc, exec, s[26:27]
	s_cbranch_vccz .LBB0_590
	s_barrier

.LBB0_727:
	s_add_u32 s41, s16, 0x100
	s_addc_u32 s10, s17, 0
	s_add_u32 s8, s38, 0x158080
	s_addc_u32 s9, s39, 0
	s_waitcnt lgkmcnt(0)
	v_lshl_add_u64 v[134:135], s[8:9], 0, v[204:205]
	v_lshl_add_u64 v[136:137], s[8:9], 0, v[206:207]
	v_add_u32_e32 v200, 0x10000, v234
	v_add_u32_e32 v201, 0x14000, v234
	v_add_u32_e32 v202, 0x18000, v234
	v_add_u32_e32 v203, 0x1c000, v234
	s_mov_b32 s11, -2
	s_mov_b64 s[8:9], 0
	s_waitcnt vmcnt(0)
.LBB0_728:
	s_add_u32 s86, s38, s8
	s_addc_u32 s87, s39, s9
	s_add_u32 s86, s86, 0x158080
	s_addc_u32 s87, s87, 0
	s_add_u32 s16, s38, s8
	s_addc_u32 s17, s39, s9
	s_add_u32 s16, s16, 0x100
	s_addc_u32 s17, s17, 0
	s_add_u32 s34, s41, s8
	s_addc_u32 s64, s10, s9
	s_add_i32 s65, 0, 0x10000
	s_cmpk_eq_i32 s8, 0x2a00
	s_cselect_b32 s49, s53, s17
	s_cselect_b32 s48, s52, s16
	s_cselect_b32 s17, s61, s64
	s_cselect_b32 s16, s60, s34
	s_add_i32 s34, 0, 0x14000
	ds_read_b128 v[138:141], v200
	ds_read_b128 v[142:145], v200 offset:1024
	ds_read_b128 v[146:149], v200 offset:2048
	ds_read_b128 v[150:153], v200 offset:3072
	ds_read_b128 v[154:157], v201
	ds_read_b128 v[158:161], v201 offset:1024
	ds_read_b128 v[162:165], v201 offset:2048
	ds_read_b128 v[166:169], v201 offset:3072
	s_add_i32 m0, s67, 0xc000
	ds_read_b128 v[170:173], v238
	ds_read_b128 v[174:177], v238 offset:1024
	ds_read_b128 v[178:181], v238 offset:2048
	ds_read_b128 v[182:185], v238 offset:3072
	ds_read_b128 v[186:189], v238 offset:4096
	ds_read_b128 v[190:193], v238 offset:5120
	ds_read_b128 v[194:197], v238 offset:6144
	ds_read_b128 v[208:211], v238 offset:7168
	global_load_lds_dwordx4 v206, s[86:87]
	s_add_i32 m0, s67, 0xe000
	s_nop 0
	global_load_lds_dwordx4 v204, s[86:87]
	s_waitcnt vmcnt(8)
	s_waitcnt lgkmcnt(0)
	s_barrier
	s_setprio 1
	s_waitcnt lgkmcnt(0)
	v_mfma_f32_16x16x32_bf16 v[6:9], v[138:141], v[170:173], v[6:9]
	v_mfma_f32_16x16x32_bf16 v[130:133], v[146:149], v[170:173], v[130:133]
	v_mfma_f32_16x16x32_bf16 v[126:129], v[138:141], v[178:181], v[126:129]
	v_mfma_f32_16x16x32_bf16 v[122:125], v[146:149], v[178:181], v[122:125]
	v_mfma_f32_16x16x32_bf16 v[118:121], v[138:141], v[186:189], v[118:121]
	v_mfma_f32_16x16x32_bf16 v[114:117], v[146:149], v[186:189], v[114:117]
	v_mfma_f32_16x16x32_bf16 v[110:113], v[138:141], v[194:197], v[110:113]
	v_mfma_f32_16x16x32_bf16 v[106:109], v[146:149], v[194:197], v[106:109]
	v_mfma_f32_16x16x32_bf16 v[6:9], v[142:145], v[174:177], v[6:9]
	v_mfma_f32_16x16x32_bf16 v[130:133], v[150:153], v[174:177], v[130:133]
	v_mfma_f32_16x16x32_bf16 v[126:129], v[142:145], v[182:185], v[126:129]
	v_mfma_f32_16x16x32_bf16 v[122:125], v[150:153], v[182:185], v[122:125]
	v_mfma_f32_16x16x32_bf16 v[118:121], v[142:145], v[190:193], v[118:121]
	v_mfma_f32_16x16x32_bf16 v[114:117], v[150:153], v[190:193], v[114:117]
	v_mfma_f32_16x16x32_bf16 v[110:113], v[142:145], v[208:211], v[110:113]
	v_mfma_f32_16x16x32_bf16 v[106:109], v[150:153], v[208:211], v[106:109]
	s_setprio 0
	s_setprio 1
	v_mfma_f32_16x16x32_bf16 v[102:105], v[154:157], v[170:173], v[102:105]
	v_mfma_f32_16x16x32_bf16 v[98:101], v[162:165], v[170:173], v[98:101]
	v_mfma_f32_16x16x32_bf16 v[94:97], v[154:157], v[178:181], v[94:97]
	v_mfma_f32_16x16x32_bf16 v[90:93], v[162:165], v[178:181], v[90:93]
	v_mfma_f32_16x16x32_bf16 v[86:89], v[154:157], v[186:189], v[86:89]
	v_mfma_f32_16x16x32_bf16 v[82:85], v[162:165], v[186:189], v[82:85]
	v_mfma_f32_16x16x32_bf16 v[78:81], v[154:157], v[194:197], v[78:81]
	v_mfma_f32_16x16x32_bf16 v[74:77], v[162:165], v[194:197], v[74:77]
	v_mfma_f32_16x16x32_bf16 v[102:105], v[158:161], v[174:177], v[102:105]
	v_mfma_f32_16x16x32_bf16 v[98:101], v[166:169], v[174:177], v[98:101]
	v_mfma_f32_16x16x32_bf16 v[94:97], v[158:161], v[182:185], v[94:97]
	v_mfma_f32_16x16x32_bf16 v[90:93], v[166:169], v[182:185], v[90:93]
	v_mfma_f32_16x16x32_bf16 v[86:89], v[158:161], v[190:193], v[86:89]
	v_mfma_f32_16x16x32_bf16 v[82:85], v[166:169], v[190:193], v[82:85]
	v_mfma_f32_16x16x32_bf16 v[78:81], v[158:161], v[208:211], v[78:81]
	v_mfma_f32_16x16x32_bf16 v[74:77], v[166:169], v[208:211], v[74:77]
	s_setprio 0
	s_barrier
	s_add_i32 s64, s65, s66
	s_mov_b32 m0, s64
	ds_read_b128 v[170:173], v238 offset:16384
	ds_read_b128 v[174:177], v238 offset:17408
	ds_read_b128 v[178:181], v238 offset:18432
	ds_read_b128 v[182:185], v238 offset:19456
	ds_read_b128 v[186:189], v238 offset:20480
	ds_read_b128 v[190:193], v238 offset:21504
	ds_read_b128 v[194:197], v238 offset:22528
	ds_read_b128 v[208:211], v238 offset:23552
	global_load_lds_dwordx4 v0, s[16:17]
	s_add_i32 m0, s64, 0x2000
	s_add_u32 s64, s16, 0x158000
	s_addc_u32 s65, s17, 0
	s_add_i32 s34, s34, s66
	global_load_lds_dwordx4 v14, s[16:17]
	s_mov_b32 m0, s34
	s_add_u32 s98, s48, s96
	s_addc_u32 s99, s49, s97
	global_load_lds_dwordx4 v0, s[64:65]
	s_add_i32 m0, s34, 0x2000
	s_nop 0
	global_load_lds_dwordx4 v14, s[64:65]
	s_mov_b32 m0, s67
	s_nop 0
	global_load_lds_dwordx4 v0, s[48:49]
	s_mov_b32 m0, s68
	s_nop 0
	global_load_lds_dwordx4 v14, s[48:49]
	s_waitcnt vmcnt(8)
	s_waitcnt lgkmcnt(0)
	s_barrier
	s_setprio 1
	s_waitcnt lgkmcnt(0)
	v_mfma_f32_16x16x32_bf16 v[70:73], v[138:141], v[170:173], v[70:73]
	v_mfma_f32_16x16x32_bf16 v[66:69], v[146:149], v[170:173], v[66:69]
	v_mfma_f32_16x16x32_bf16 v[62:65], v[138:141], v[178:181], v[62:65]
	v_mfma_f32_16x16x32_bf16 v[58:61], v[146:149], v[178:181], v[58:61]
	v_mfma_f32_16x16x32_bf16 v[54:57], v[138:141], v[186:189], v[54:57]
	v_mfma_f32_16x16x32_bf16 v[50:53], v[146:149], v[186:189], v[50:53]
	v_mfma_f32_16x16x32_bf16 v[46:49], v[138:141], v[194:197], v[46:49]
	v_mfma_f32_16x16x32_bf16 v[42:45], v[146:149], v[194:197], v[42:45]
	v_mfma_f32_16x16x32_bf16 v[70:73], v[142:145], v[174:177], v[70:73]
	v_mfma_f32_16x16x32_bf16 v[66:69], v[150:153], v[174:177], v[66:69]
	v_mfma_f32_16x16x32_bf16 v[62:65], v[142:145], v[182:185], v[62:65]
	v_mfma_f32_16x16x32_bf16 v[58:61], v[150:153], v[182:185], v[58:61]
	v_mfma_f32_16x16x32_bf16 v[54:57], v[142:145], v[190:193], v[54:57]
	v_mfma_f32_16x16x32_bf16 v[50:53], v[150:153], v[190:193], v[50:53]
	v_mfma_f32_16x16x32_bf16 v[46:49], v[142:145], v[208:211], v[46:49]
	v_mfma_f32_16x16x32_bf16 v[42:45], v[150:153], v[208:211], v[42:45]
	s_setprio 0
	s_setprio 1
	v_mfma_f32_16x16x32_bf16 v[38:41], v[154:157], v[170:173], v[38:41]
	v_mfma_f32_16x16x32_bf16 v[34:37], v[162:165], v[170:173], v[34:37]
	v_mfma_f32_16x16x32_bf16 v[30:33], v[154:157], v[178:181], v[30:33]
	v_mfma_f32_16x16x32_bf16 v[26:29], v[162:165], v[178:181], v[26:29]
	v_mfma_f32_16x16x32_bf16 v[22:25], v[154:157], v[186:189], v[22:25]
	v_mfma_f32_16x16x32_bf16 v[18:21], v[162:165], v[186:189], v[18:21]
	v_mfma_f32_16x16x32_bf16 v[10:13], v[154:157], v[194:197], v[10:13]
	v_mfma_f32_16x16x32_bf16 v[2:5], v[162:165], v[194:197], v[2:5]
	v_mfma_f32_16x16x32_bf16 v[38:41], v[158:161], v[174:177], v[38:41]
	v_mfma_f32_16x16x32_bf16 v[34:37], v[166:169], v[174:177], v[34:37]
	v_mfma_f32_16x16x32_bf16 v[30:33], v[158:161], v[182:185], v[30:33]
	v_mfma_f32_16x16x32_bf16 v[26:29], v[166:169], v[182:185], v[26:29]
	v_mfma_f32_16x16x32_bf16 v[22:25], v[158:161], v[190:193], v[22:25]
	v_mfma_f32_16x16x32_bf16 v[18:21], v[166:169], v[190:193], v[18:21]
	v_mfma_f32_16x16x32_bf16 v[10:13], v[158:161], v[208:211], v[10:13]
	v_mfma_f32_16x16x32_bf16 v[2:5], v[166:169], v[208:211], v[2:5]
	s_setprio 0
	s_barrier
	s_add_i32 s34, 0, 0x18000
	s_add_i32 s64, 0, 0x1c000
	ds_read_b128 v[138:141], v202
	ds_read_b128 v[142:145], v202 offset:1024
	ds_read_b128 v[146:149], v202 offset:2048
	ds_read_b128 v[150:153], v202 offset:3072
	ds_read_b128 v[154:157], v203
	ds_read_b128 v[158:161], v203 offset:1024
	ds_read_b128 v[162:165], v203 offset:2048
	ds_read_b128 v[166:169], v203 offset:3072
	s_add_u32 s48, s48, 0x158000
	s_addc_u32 s49, s49, 0
	s_mov_b32 m0, s69
	ds_read_b128 v[170:173], v238 offset:32768
	ds_read_b128 v[174:177], v238 offset:33792
	ds_read_b128 v[178:181], v238 offset:34816
	ds_read_b128 v[182:185], v238 offset:35840
	ds_read_b128 v[186:189], v238 offset:36864
	ds_read_b128 v[190:193], v238 offset:37888
	ds_read_b128 v[194:197], v238 offset:38912
	ds_read_b128 v[208:211], v238 offset:39936
	global_load_lds_dwordx4 v0, s[48:49]
	s_mov_b32 m0, s70
	s_nop 0
	global_load_lds_dwordx4 v14, s[48:49]
	s_waitcnt vmcnt(8)
	s_waitcnt lgkmcnt(0)
	s_barrier
	s_setprio 1
	s_waitcnt lgkmcnt(0)
	v_mfma_f32_16x16x32_bf16 v[6:9], v[138:141], v[170:173], v[6:9]
	v_mfma_f32_16x16x32_bf16 v[130:133], v[146:149], v[170:173], v[130:133]
	v_mfma_f32_16x16x32_bf16 v[126:129], v[138:141], v[178:181], v[126:129]
	v_mfma_f32_16x16x32_bf16 v[122:125], v[146:149], v[178:181], v[122:125]
	v_mfma_f32_16x16x32_bf16 v[118:121], v[138:141], v[186:189], v[118:121]
	v_mfma_f32_16x16x32_bf16 v[114:117], v[146:149], v[186:189], v[114:117]
	v_mfma_f32_16x16x32_bf16 v[110:113], v[138:141], v[194:197], v[110:113]
	v_mfma_f32_16x16x32_bf16 v[106:109], v[146:149], v[194:197], v[106:109]
	v_mfma_f32_16x16x32_bf16 v[6:9], v[142:145], v[174:177], v[6:9]
	v_mfma_f32_16x16x32_bf16 v[130:133], v[150:153], v[174:177], v[130:133]
	v_mfma_f32_16x16x32_bf16 v[126:129], v[142:145], v[182:185], v[126:129]
	v_mfma_f32_16x16x32_bf16 v[122:125], v[150:153], v[182:185], v[122:125]
	v_mfma_f32_16x16x32_bf16 v[118:121], v[142:145], v[190:193], v[118:121]
	v_mfma_f32_16x16x32_bf16 v[114:117], v[150:153], v[190:193], v[114:117]
	v_mfma_f32_16x16x32_bf16 v[110:113], v[142:145], v[208:211], v[110:113]
	v_mfma_f32_16x16x32_bf16 v[106:109], v[150:153], v[208:211], v[106:109]
	s_setprio 0
	s_setprio 1
	v_mfma_f32_16x16x32_bf16 v[102:105], v[154:157], v[170:173], v[102:105]
	v_mfma_f32_16x16x32_bf16 v[98:101], v[162:165], v[170:173], v[98:101]
	v_mfma_f32_16x16x32_bf16 v[94:97], v[154:157], v[178:181], v[94:97]
	v_mfma_f32_16x16x32_bf16 v[90:93], v[162:165], v[178:181], v[90:93]
	v_mfma_f32_16x16x32_bf16 v[86:89], v[154:157], v[186:189], v[86:89]
	v_mfma_f32_16x16x32_bf16 v[82:85], v[162:165], v[186:189], v[82:85]
	v_mfma_f32_16x16x32_bf16 v[78:81], v[154:157], v[194:197], v[78:81]
	v_mfma_f32_16x16x32_bf16 v[74:77], v[162:165], v[194:197], v[74:77]
	v_mfma_f32_16x16x32_bf16 v[102:105], v[158:161], v[174:177], v[102:105]
	v_mfma_f32_16x16x32_bf16 v[98:101], v[166:169], v[174:177], v[98:101]
	v_mfma_f32_16x16x32_bf16 v[94:97], v[158:161], v[182:185], v[94:97]
	v_mfma_f32_16x16x32_bf16 v[90:93], v[166:169], v[182:185], v[90:93]
	v_mfma_f32_16x16x32_bf16 v[86:89], v[158:161], v[190:193], v[86:89]
	v_mfma_f32_16x16x32_bf16 v[82:85], v[166:169], v[190:193], v[82:85]
	v_mfma_f32_16x16x32_bf16 v[78:81], v[158:161], v[208:211], v[78:81]
	v_mfma_f32_16x16x32_bf16 v[74:77], v[166:169], v[208:211], v[74:77]
	s_setprio 0
	s_barrier
	s_add_i32 s34, s34, s66
	s_add_u32 s86, s16, s96
	s_addc_u32 s87, s17, s97
	s_mov_b32 m0, s34
	ds_read_b128 v[170:173], v238 offset:49152
	ds_read_b128 v[174:177], v238 offset:50176
	ds_read_b128 v[178:181], v238 offset:51200
	ds_read_b128 v[182:185], v238 offset:52224
	ds_read_b128 v[186:189], v238 offset:53248
	ds_read_b128 v[190:193], v238 offset:54272
	ds_read_b128 v[194:197], v238 offset:55296
	ds_read_b128 v[208:211], v238 offset:56320
	global_load_lds_dwordx4 v0, s[86:87]
	s_add_i32 m0, s34, 0x2000
	s_add_u32 s16, s16, 0x158080
	s_addc_u32 s17, s17, 0
	s_add_i32 s34, s64, s66
	global_load_lds_dwordx4 v14, s[86:87]
	s_mov_b32 m0, s34
	s_nop 0
	global_load_lds_dwordx4 v0, s[16:17]
	s_add_i32 m0, s34, 0x2000
	s_nop 0
	global_load_lds_dwordx4 v14, s[16:17]
	s_mov_b32 m0, s76
	s_nop 0
	global_load_lds_dwordx4 v0, s[98:99]
	s_mov_b32 m0, s77
	s_nop 0
	global_load_lds_dwordx4 v14, s[98:99]
	s_waitcnt vmcnt(8)
	s_waitcnt lgkmcnt(0)
	s_barrier
	s_setprio 1
	s_waitcnt lgkmcnt(0)
	v_mfma_f32_16x16x32_bf16 v[70:73], v[138:141], v[170:173], v[70:73]
	v_mfma_f32_16x16x32_bf16 v[66:69], v[146:149], v[170:173], v[66:69]
	v_mfma_f32_16x16x32_bf16 v[62:65], v[138:141], v[178:181], v[62:65]
	v_mfma_f32_16x16x32_bf16 v[58:61], v[146:149], v[178:181], v[58:61]
	v_mfma_f32_16x16x32_bf16 v[54:57], v[138:141], v[186:189], v[54:57]
	v_mfma_f32_16x16x32_bf16 v[50:53], v[146:149], v[186:189], v[50:53]
	v_mfma_f32_16x16x32_bf16 v[46:49], v[138:141], v[194:197], v[46:49]
	v_mfma_f32_16x16x32_bf16 v[42:45], v[146:149], v[194:197], v[42:45]
	v_mfma_f32_16x16x32_bf16 v[70:73], v[142:145], v[174:177], v[70:73]
	v_mfma_f32_16x16x32_bf16 v[66:69], v[150:153], v[174:177], v[66:69]
	v_mfma_f32_16x16x32_bf16 v[62:65], v[142:145], v[182:185], v[62:65]
	v_mfma_f32_16x16x32_bf16 v[58:61], v[150:153], v[182:185], v[58:61]
	v_mfma_f32_16x16x32_bf16 v[54:57], v[142:145], v[190:193], v[54:57]
	v_mfma_f32_16x16x32_bf16 v[50:53], v[150:153], v[190:193], v[50:53]
	v_mfma_f32_16x16x32_bf16 v[46:49], v[142:145], v[208:211], v[46:49]
	v_mfma_f32_16x16x32_bf16 v[42:45], v[150:153], v[208:211], v[42:45]
	s_setprio 0
	s_setprio 1
	v_mfma_f32_16x16x32_bf16 v[38:41], v[154:157], v[170:173], v[38:41]
	v_mfma_f32_16x16x32_bf16 v[34:37], v[162:165], v[170:173], v[34:37]
	v_mfma_f32_16x16x32_bf16 v[30:33], v[154:157], v[178:181], v[30:33]
	v_mfma_f32_16x16x32_bf16 v[26:29], v[162:165], v[178:181], v[26:29]
	v_mfma_f32_16x16x32_bf16 v[22:25], v[154:157], v[186:189], v[22:25]
	v_mfma_f32_16x16x32_bf16 v[18:21], v[162:165], v[186:189], v[18:21]
	v_mfma_f32_16x16x32_bf16 v[10:13], v[154:157], v[194:197], v[10:13]
	v_mfma_f32_16x16x32_bf16 v[2:5], v[162:165], v[194:197], v[2:5]
	v_mfma_f32_16x16x32_bf16 v[38:41], v[158:161], v[174:177], v[38:41]
	v_mfma_f32_16x16x32_bf16 v[34:37], v[166:169], v[174:177], v[34:37]
	v_mfma_f32_16x16x32_bf16 v[30:33], v[158:161], v[182:185], v[30:33]
	v_mfma_f32_16x16x32_bf16 v[26:29], v[166:169], v[182:185], v[26:29]
	v_mfma_f32_16x16x32_bf16 v[22:25], v[158:161], v[190:193], v[22:25]
	v_mfma_f32_16x16x32_bf16 v[18:21], v[166:169], v[190:193], v[18:21]
	v_mfma_f32_16x16x32_bf16 v[10:13], v[158:161], v[208:211], v[10:13]
	v_mfma_f32_16x16x32_bf16 v[2:5], v[166:169], v[208:211], v[2:5]
	s_setprio 0
	s_barrier
	s_add_i32 s11, s11, 2
	s_add_u32 s8, s8, 0x100
	s_addc_u32 s9, s9, 0
	s_cmpk_gt_u32 s11, 0x53
	s_cbranch_scc0 .LBB0_728
	s_and_b64 vcc, exec, s[28:29]
	s_cbranch_vccz .LBB0_731
	s_barrier
